# GEMM1 tile order: row-group height 4 instead of 3 (4x8 tile patch per XCD round) for better L2 panel sharing
# baseline (speedup 1.0000x reference)
; __device__ __forceinline__ KP kargs() { KP q = (KP)__builtin_amdgcn_kernarg_segment_ptr(); asm volatile("" : "+s"(q)); return q; }
; __device__ __forceinline__ unsigned xb_ld(unsigned* p)              { return __hip_atomic_load(p, __ATOMIC_RELAXED, __HIP_MEMORY_SCOPE_AGENT); }
; #define REPS(i) for (int rep_ = 0; rep_ < (((REP_MASK >> (i)) & 1u) ? 2 : 1); ++rep_)
; __device__ __forceinline__ void xcd_barrier_complete(unsigned* bar, unsigned x, unsigned& nloc, unsigned& nx) {
;     const unsigned G = gridDim.x * gridDim.y * gridDim.z;
;     unsigned sum, cnt, mine, sp = 0u;
;     for (;;) {
;         sum = 0u; cnt = 0u; mine = 0u;
; #pragma unroll
;         for (unsigned j = 0; j < 16; ++j) { const unsigned c = xb_ld(&bar[XB_XCNT(j)]); sum += c; cnt += (c > 0u) ? 1u : 0u; mine = (j == x) ? c : mine; }
; __global__ void __launch_bounds__(512, 2) fwd_megakernel(Params p_unused) {
;     ...
;     const int vc = (int)bst[2];
;     for (int l = 0; l < DEPTH; ++l) {
;         const int pb = 1 + 6 * l; KP p = kargs(); unsigned char* ws = p->ws;
;         if (IN(pb + 0)) REPS(1) {
;             pg8::Gemm g{(const bf16_t*)(ws + WS_XB), (const bf16_t*)(ws + WS_WIN + l * SZ_WIN), SEQ, DIN, DM};
;             pg8::StaticOrder S; S.init(SEQ, DIN - 256, gridDim.x, vc);
;             pg8::EpiH E{(bf16_t*)(ws + WS_HM), (bf16_t*)(ws + WS_HG)};
;             pg8::gemm_phase<GEMM_ALIGN, GEMM_SP2>(lds, g, S, E);
.LBB0_212:
	s_add_i32 s3, 0, 0x23fc8
	v_mov_b32_e32 v0, s3
	s_waitcnt lgkmcnt(0)
	s_barrier
	ds_read_b32 v0, v0
	v_mov_b32_e32 v168, 1
	v_mov_b32_e32 v169, 0x3727c5ac
	v_mov_b64_e32 v[140:141], 0x1200
	v_mov_b64_e32 v[142:143], 0x11ff
	s_waitcnt lgkmcnt(0)
	v_readfirstlane_b32 s3, v0
	s_cmpk_lt_i32 s3, 0x1200
	s_cselect_b64 s[14:15], -1, 0
	s_ashr_i32 s13, s3, 31
	s_lshr_b32 s6, s13, 29
	s_add_i32 s6, s3, s6
	s_ashr_i32 s7, s6, 3
	s_and_b32 s6, s6, -8
	s_sub_i32 s6, s3, s6
	s_ashr_i32 s21, s72, 31
	s_add_u32 s48, s0, 0x3ab00200
	s_addc_u32 s49, s1, 0
	s_add_u32 s62, s0, 0x3ab00400
	s_addc_u32 s63, s1, 0
	s_add_u32 s64, s0, 0x3ab00500
	s_addc_u32 s65, s1, 0
	s_add_u32 s74, s0, 0x3ab00600
	s_addc_u32 s75, s1, 0
	s_add_u32 s10, s0, 0x3ab00700
	s_addc_u32 s11, s1, 0
	s_add_u32 s88, s0, 0x3ab00800
	s_addc_u32 s89, s1, 0
	s_add_u32 s94, s0, 0x3ab00900
	s_addc_u32 s95, s1, 0
	s_add_u32 s8, s0, 0x3ab00a00
	s_addc_u32 s9, s1, 0
	v_writelane_b32 v241, s8, 6
	v_mov_b32_e32 v170, 0x41f00000
	v_mov_b32_e32 v171, 0x4200
	v_writelane_b32 v241, s9, 7
	s_add_u32 s8, s0, 0x3ab00b00
	s_addc_u32 s9, s1, 0
	v_writelane_b32 v241, s8, 8
	v_mov_b32_e32 v173, 0xf149f2ca
	v_mov_b64_e32 v[144:145], 0x200
	v_writelane_b32 v241, s9, 9
	s_add_u32 s8, s0, 0x3ab00c00
	s_addc_u32 s9, s1, 0
	v_writelane_b32 v241, s8, 10
	v_mov_b64_e32 v[146:147], 0x1ff
	s_mov_b32 s51, 0x2aaaaaab
	v_writelane_b32 v241, s9, 11
	s_add_u32 s8, s0, 0x3ab00d00
	s_addc_u32 s9, s1, 0
	v_writelane_b32 v241, s8, 12
	s_movk_i32 s50, 0x4200
	s_movk_i32 s52, 0x3000
	v_writelane_b32 v241, s9, 13
	s_add_u32 s8, s0, 0x3ab00e00
	s_addc_u32 s9, s1, 0
	s_add_u32 s76, s0, 0x3ab00f00
	s_addc_u32 s77, s1, 0
	s_add_u32 s78, s0, 0x3ab01000
	s_addc_u32 s79, s1, 0
	s_add_u32 s80, s0, 0x3ab01100
	s_addc_u32 s81, s1, 0
	s_add_u32 s82, s0, 0x3ab01200
	s_addc_u32 s83, s1, 0
	s_add_u32 s84, s0, 0x3ab01300
	s_addc_u32 s85, s1, 0
	v_writelane_b32 v241, s8, 14
	s_cmp_eq_u32 s33, 15
	s_mov_b32 s54, 0xffff0000
	v_writelane_b32 v241, s9, 15
	s_cselect_b64 s[8:9], -1, 0
	v_writelane_b32 v241, s8, 16
	s_cmp_eq_u32 s33, 14
	s_movk_i32 s55, 0x2100
	v_writelane_b32 v241, s9, 17
	s_cselect_b64 s[8:9], -1, 0
	v_writelane_b32 v241, s8, 18
	s_cmp_eq_u32 s33, 13
	s_mov_b32 s56, 0x800000
	v_writelane_b32 v241, s9, 19
	s_cselect_b64 s[8:9], -1, 0
	v_writelane_b32 v241, s8, 20
	s_cmp_eq_u32 s33, 12
	s_mov_b32 s57, 0xffff
	v_writelane_b32 v241, s9, 21
	s_cselect_b64 s[8:9], -1, 0
	v_writelane_b32 v241, s8, 22
	s_cmp_eq_u32 s33, 11
	s_movk_i32 s58, 0x1ff
	v_writelane_b32 v241, s9, 23
	s_cselect_b64 s[8:9], -1, 0
	v_writelane_b32 v241, s8, 24
	s_cmp_eq_u32 s33, 10
	s_movk_i32 s67, 0x230
	v_writelane_b32 v241, s9, 25
	s_cselect_b64 s[8:9], -1, 0
	v_writelane_b32 v241, s8, 26
	s_cmp_eq_u32 s33, 9
	s_mov_b32 s59, 0x44000
	v_writelane_b32 v241, s9, 27
	s_cselect_b64 s[8:9], -1, 0
	v_writelane_b32 v241, s8, 28
	s_cmp_eq_u32 s33, 8
	s_mov_b32 s60, 0x5040100
	v_writelane_b32 v241, s9, 29
	s_cselect_b64 s[8:9], -1, 0
	v_writelane_b32 v241, s8, 30
	s_cmp_eq_u32 s33, 7
	s_mov_b64 s[16:17], 0x2000
	v_writelane_b32 v241, s9, 31
	s_cselect_b64 s[8:9], -1, 0
	v_writelane_b32 v241, s8, 32
	s_cmp_eq_u32 s33, 6
	s_mov_b64 s[18:19], 0x2a00
	v_writelane_b32 v241, s9, 33
	s_cselect_b64 s[8:9], -1, 0
	v_writelane_b32 v241, s8, 34
	s_cmp_eq_u32 s33, 5
	s_mov_b32 s20, 0x3fb504f3
	v_writelane_b32 v241, s9, 35
	s_cselect_b64 s[8:9], -1, 0
	v_writelane_b32 v241, s8, 36
	s_cmp_eq_u32 s33, 4
	s_nop 0
	v_writelane_b32 v241, s9, 37
	s_cselect_b64 s[8:9], -1, 0
	v_writelane_b32 v241, s8, 38
	s_cmp_eq_u32 s33, 3
	s_nop 0
	v_writelane_b32 v241, s9, 39
	s_cselect_b64 s[8:9], -1, 0
	v_writelane_b32 v241, s8, 40
	s_cmp_eq_u32 s33, 2
	s_nop 0
	v_writelane_b32 v241, s9, 41
	s_cselect_b64 s[8:9], -1, 0
	v_writelane_b32 v241, s8, 42
	s_cmp_eq_u32 s33, 1
	s_nop 0
	v_writelane_b32 v241, s9, 43
	s_cselect_b64 s[8:9], -1, 0
	v_writelane_b32 v241, s8, 44
	s_cmp_eq_u32 s33, 0
	s_nop 0
	v_writelane_b32 v241, s9, 45
	s_cselect_b64 s[8:9], -1, 0
	v_writelane_b32 v241, s8, 46
	s_nop 1
	v_writelane_b32 v241, s9, 47
	s_lshl_b32 s8, s33, 8
	s_add_u32 s8, s86, s8
	s_addc_u32 s9, s87, 0
	s_mov_b64 s[86:87], s[10:11]
	s_add_u32 s10, s8, 0x1400
	s_addc_u32 s11, s9, 0
	v_writelane_b32 v241, s10, 48
	s_add_u32 s8, s8, 0x2400
	s_addc_u32 s9, s9, 0
	v_writelane_b32 v241, s11, 49
	v_writelane_b32 v241, s8, 50
;     __device__ bool next(int i, Unit& u) const { if (i != 0) return false; u.pm = pm; u.pn = pn; return true; }
;     __device__ bool next(int i, Unit& u) const { const int L = i * G + c; if (L >= 256) return false; u.pm = L; u.pn = L >> 6; return true; }
;     __device__ bool next(int i, Unit& u) const { Unit t; if (!so.next(i >> 2, t)) return false; const int b = i & 3; u.pm = b * 64 + t.pm; u.pn = b * 8 + t.pn; return true; }
;     __device__ bool next(int i, Unit& u) const {
;         const long L = (long)i * G + c; if (L >= limit) return false;
;         int wgid = (int)L; { const int q = nwg / NXCD, r = nwg % NXCD, xcd = wgid % NXCD, off = wgid / NXCD; wgid = (xcd < r ? xcd * (q + 1) : r * (q + 1) + (xcd - r) * q) + off; }
;         const int nig = WGM * nN, gid = wgid / nig, fm = gid * WGM, gsz = (nM - fm) < WGM ? (nM - fm) : WGM;
;         u.pm = fm + ((wgid % nig) % gsz); u.pn = (wgid % nig) / gsz; return true;
	s_movk_i32 s33, 0x2000
	s_nop 0
	v_writelane_b32 v241, s9, 51
	s_add_u32 s8, s0, 0x3ab03400
	s_addc_u32 s9, s1, 0
	v_writelane_b32 v241, s8, 52
	s_add_u32 s0, s0, 0x3ab03500
	s_addc_u32 s1, s1, 0
	v_writelane_b32 v241, s9, 53
	v_writelane_b32 v241, s0, 54
	s_nop 1
	v_writelane_b32 v241, s1, 55
	s_nop 0
	v_readlane_b32 s0, v241, 0
	v_readlane_b32 s1, v241, 1
	s_cmpk_lt_i32 s0, 0x100
	s_mov_b32 s8, s0
	s_cselect_b64 s[0:1], -1, 0
	v_writelane_b32 v241, s0, 56
	s_nop 1
	v_writelane_b32 v241, s1, 57
	s_ashr_i32 s1, s8, 31
	s_ashr_i32 s0, s8, 6
	v_writelane_b32 v241, s1, 58
	v_writelane_b32 v241, s0, 59
	s_ashr_i32 s0, s0, 31
	s_cmpk_lt_i32 s3, 0x200
	v_writelane_b32 v241, s0, 60
	s_cselect_b64 s[0:1], -1, 0
	v_writelane_b32 v241, s0, 61
	s_nop 1
	v_writelane_b32 v241, s1, 62
	s_lshl_b32 s1, s8, 3
	v_writelane_b32 v241, s1, 63
	s_lshl_b32 s1, s72, 3
	s_lshl_b32 s0, s6, 6
	v_writelane_b32 v240, s1, 0
	v_readlane_b32 s1, v241, 2
	s_cmp_gt_i32 s1, 7
	s_cselect_b64 s[8:9], -1, 0
	s_cmp_lt_i32 s6, 0
	s_movk_i32 s1, 0x241
	s_cselect_b32 s1, s1, 0x240
	s_mul_i32 s1, s6, s1
	s_mulk_i32 s6, 0x41
	s_cselect_b32 s0, s6, s0
	s_add_i32 s1, s1, s7
	v_writelane_b32 v240, s8, 1
	s_mul_hi_i32 s6, s1, 0x4bda12f7
	s_add_i32 s0, s0, s7
	v_writelane_b32 v240, s9, 2
	s_lshr_b32 s8, s6, 31
	s_ashr_i32 s6, s6, 6
	s_add_i32 s6, s6, s8
	s_mul_i32 s8, s6, 0xd8
	s_sub_i32 s8, s1, s8
	s_mul_hi_i32 s1, s0, 0x2aaaaaab
	s_lshr_b32 s7, s1, 31
	s_ashr_i32 s1, s1, 2
	s_add_i32 s1, s1, s7
	s_mul_i32 s7, s1, 24
	s_mul_i32 s6, s6, 3
	s_sub_i32 s7, s0, s7
	s_sub_i32 s0, 64, s6
	s_min_u32 s9, s0, 3
	v_cvt_f32_ubyte0_e32 v1, s9
	v_cvt_f32_i32_e32 v0, s8
	v_rcp_iflag_f32_e32 v2, v1
	s_mul_i32 s10, s1, 3
	s_sub_i32 s0, 64, s10
	s_min_u32 s11, s0, 3
	v_mul_f32_e32 v2, v0, v2
	v_trunc_f32_e32 v2, v2
	s_ashr_i32 s0, s8, 30
	v_fma_f32 v0, -v2, v1, v0
	s_or_b32 s12, s0, 1
	v_cmp_ge_f32_e64 s[0:1], |v0|, v1
	v_cvt_i32_f32_e32 v0, v2
	s_and_b64 s[0:1], s[0:1], exec
	v_cvt_f32_ubyte0_e32 v1, s11
	s_cselect_b32 s0, s12, 0
	v_readfirstlane_b32 s1, v0
	v_cvt_f32_i32_e32 v0, s7
	v_rcp_iflag_f32_e32 v2, v1
	s_add_i32 s12, s1, s0
	s_mul_i32 s0, s12, s9
	s_sub_i32 s0, s8, s0
	s_sext_i32_i16 s0, s0
	v_mul_f32_e32 v2, v0, v2
	s_mul_i32 s0, s6, 0x48
	s_add_i32 s0, s0, s8
	s_mul_i32 s1, s0, 0xe38f
	s_lshr_b32 s1, s1, 24
	s_mul_i32 s12, s1, 0x120
	s_sub_i32 s0, s0, s12
	s_lshr_b32 s12, s0, 2
	s_and_b32 s0, s0, 3
	s_lshl_b32 s1, s1, 2
	s_add_i32 s0, s0, s1
	v_trunc_f32_e32 v2, v2
	v_writelane_b32 v240, s0, 3
	s_ashr_i32 s0, s7, 30
	v_fma_f32 v0, -v2, v1, v0
	s_or_b32 s6, s0, 1
	v_cmp_ge_f32_e64 s[0:1], |v0|, v1
	v_cvt_i32_f32_e32 v0, v2
	s_and_b64 s[0:1], s[0:1], exec
	v_writelane_b32 v240, s14, 4
	s_mul_i32 s0, s73, s72
	s_mul_i32 s0, s0, s2
	v_writelane_b32 v240, s15, 5
	v_writelane_b32 v240, s0, 6
	s_cselect_b32 s0, s6, 0
	v_readfirstlane_b32 s1, v0
	s_add_i32 s0, s1, s0
	s_mul_i32 s1, s0, s11
	s_sub_i32 s1, s7, s1
	s_sext_i32_i8 s1, s1
	s_sext_i32_i16 s2, s12
	s_add_i32 s1, s10, s1
	v_writelane_b32 v240, s2, 7
	v_writelane_b32 v240, s1, 8
	s_ashr_i32 s1, s1, 31
	s_sext_i32_i8 s0, s0
	v_writelane_b32 v240, s1, 9
	v_writelane_b32 v240, s0, 10
	s_ashr_i32 s0, s0, 31
	v_writelane_b32 v240, s0, 11
	s_add_i32 s0, 0, 0x23fc0
	v_writelane_b32 v240, s0, 12
	s_add_i32 s0, 0, 0x23fc4
	v_writelane_b32 v240, s0, 13
	s_add_i32 s0, 0, 0x9200
	v_writelane_b32 v240, s0, 14
	s_add_i32 s0, 0, 0x12400
	v_writelane_b32 v240, s0, 15
	s_add_i32 s0, 0, 0x11c00
	v_writelane_b32 v240, s0, 16
	s_mov_b64 s[0:1], -1
	v_writelane_b32 v240, s0, 17
	v_mbcnt_lo_u32_b32 v0, -1, 0
	s_mov_b32 s7, 0
	v_writelane_b32 v240, s1, 18
	v_writelane_b32 v240, s48, 19
	v_cndmask_b32_e64 v167, 0, 1, s[14:15]
	v_mov_b32_e32 v1, 0
	v_writelane_b32 v240, s49, 20
	v_writelane_b32 v240, s62, 21
	v_mbcnt_hi_u32_b32 v172, -1, v0
	s_mov_b32 s73, 0xc1f00000
	v_writelane_b32 v240, s63, 22
	v_writelane_b32 v240, s64, 23
	s_movk_i32 s2, 0x1000
	s_add_i32 s53, 0, 0x23fe0
	v_writelane_b32 v240, s65, 24
	v_writelane_b32 v240, s74, 25
	s_mov_b64 s[8:9], 0x80
	s_mov_b64 s[10:11], 0x1000
	v_writelane_b32 v240, s75, 26
	v_writelane_b32 v240, s86, 27
	s_mov_b32 s12, 0x3a800000
	s_mov_b32 s6, s7
	v_writelane_b32 v240, s87, 28
	v_writelane_b32 v240, s88, 29
	s_nop 1
	v_writelane_b32 v240, s89, 30
	v_writelane_b32 v240, s94, 31
	s_nop 1
	v_writelane_b32 v240, s95, 32
	s_branch .LBB0_216

;     __device__ bool next(int i, Unit& u) const { if (i != 0) return false; u.pm = pm; u.pn = pn; return true; }
;     __device__ bool next(int i, Unit& u) const { const int L = i * G + c; if (L >= 256) return false; u.pm = L; u.pn = L >> 6; return true; }
;     __device__ bool next(int i, Unit& u) const { Unit t; if (!so.next(i >> 2, t)) return false; const int b = i & 3; u.pm = b * 64 + t.pm; u.pn = b * 8 + t.pn; return true; }
;     __device__ bool next(int i, Unit& u) const {
;         const long L = (long)i * G + c; if (L >= limit) return false;
;         int wgid = (int)L; { const int q = nwg / NXCD, r = nwg % NXCD, xcd = wgid % NXCD, off = wgid / NXCD; wgid = (xcd < r ? xcd * (q + 1) : r * (q + 1) + (xcd - r) * q) + off; }
;         const int nig = WGM * nN, gid = wgid / nig, fm = gid * WGM, gsz = (nM - fm) < WGM ? (nM - fm) : WGM;
;         u.pm = fm + ((wgid % nig) % gsz); u.pn = (wgid % nig) / gsz; return true;
.LBB0_227:
	s_add_i32 s66, s66, 1
	s_mul_i32 s24, s66, s21
	s_mul_hi_u32 s40, s66, s72
	s_add_i32 s24, s40, s24
	s_mul_i32 s40, s66, s72
	s_add_u32 s40, s40, s3
	s_addc_u32 s41, s24, s13
	v_cmp_gt_i64_e32 vcc, s[40:41], v[142:143]
	v_cmp_lt_i64_e64 s[42:43], s[40:41], v[140:141]
	s_cbranch_vccnz .LBB0_229
	s_ashr_i32 s24, s40, 31
	s_lshr_b32 s24, s24, 29
	s_add_i32 s24, s40, s24
	s_ashr_i32 s41, s24, 3
	s_and_b32 s24, s24, -8
	s_sub_i32 s24, s40, s24
	s_cmp_lt_i32 s24, 0
	s_cselect_b32 s40, s74, 0x240
	s_mul_i32 s24, s24, s40
	s_add_i32 s24, s24, s41
	s_mul_i32 s40, s24, 0xe38f
	s_lshr_b32 s40, s40, 24
	s_mul_i32 s41, s40, 0x120
	s_sub_i32 s24, s24, s41
	s_lshr_b32 s67, s24, 2
	s_and_b32 s24, s24, 3
	s_lshl_b32 s40, s40, 2
	s_add_i32 s68, s40, s24
